# v010 + one static s_setprio 1 for waves 4-7 during the attention task loop (reset to 0 at the loop exit)
# speedup vs baseline: 1.0067x; 1.0016x over previous
; template <int DRY>
; __device__ __forceinline__ void attn_task(LAS unsigned char* vl, LAS const f32x4* ctf, LAS const float* cfar, const bf16_t* MG, bf16_t* OD, int opitch, const bf16_t* Kb, const bf16_t* Vb, float* ssqa, int task, int lane) {
;     const int fr = lane & 15, fq = lane >> 4;
;     const int r4 = task & 3, jb = (task >> 2) & 31, bh = task >> 7;
;     const int h = bh % NHEAD, b = bh / NHEAD;
;     const int j0 = jb * 64;
;     const int rowbase = b * SEQ;
;     AttnCtx C; C.r4 = r4; C.j0 = j0; C.rowbase = rowbase; C.h = h; C.lane = lane; C.vl = vl; C.ctf = ctf; C.cfar = cfar;
;     C.klo = (4 * fr * AW + 8 * fq) * 2; C.vlo = (4 * (lane >> 2) * AW + 8 * (lane & 3)) * 2;
;     C.Kr = __builtin_amdgcn_make_buffer_rsrc((void*)Kb, (short)0, MTOK * AW * 2, 0x00020000); C.Vr = __builtin_amdgcn_make_buffer_rsrc((void*)Vb, (short)0, MTOK * AW * 2, 0x00020000);
;     AttnLane L; { const int rs = fr & 3; L.s0 = rs == 0; L.s1 = rs == 1; L.s2 = rs == 2; L.mx = rs == 0 ? 0x0000ffffu : (rs == 1 ? 0xffff0000u : 0u); L.my = rs == 2 ? 0x0000ffffu : (rs == 3 ? 0xffff0000u : 0u); }
.LBB0_543:
	s_lshl_b32 s0, s1, 13
	s_add_i32 s59, s0, 0
	s_cmp_lt_u32 s1, 4
	s_cbranch_scc1 .Lmy_attn_prio_done
	s_setprio 1
.Lmy_attn_prio_done:
	v_bfe_u32 v2, v139, 4, 2
	s_add_u32 s8, s18, 0x2b400000
	v_mul_u32_u24_e32 v3, 0x1800, v5
	v_lshlrev_b32_e32 v0, 3, v2
	v_and_b32_e32 v1, 63, v139
	s_addc_u32 s2, s19, 0
	v_or_b32_e32 v3, v0, v3
	v_and_b32_e32 v6, 60, v139
	v_lshlrev_b32_e32 v7, 3, v139
	v_mul_u32_u24_e32 v6, 0x600, v6
	v_and_b32_e32 v7, 24, v7
	v_lshlrev_b32_e32 v184, 1, v3
	s_and_b32 s9, s2, 0xffff
	v_lshlrev_b32_e32 v3, 4, v1
	s_add_i32 s2, 0, 0x10000
	v_or_b32_e32 v6, v7, v6
	v_add_u32_e32 v188, s2, v3
	v_cmp_eq_u32_e64 s[2:3], 2, v4
	v_mov_b32_e32 v8, 0xffff0000
	v_cmp_eq_u32_e32 vcc, 1, v4
	v_cmp_eq_u32_e64 s[0:1], 3, v4
	v_lshlrev_b32_e32 v182, 1, v6
	v_and_b32_e32 v6, 0x3c0, v3
	v_cndmask_b32_e64 v3, 3, 2, s[2:3]
	s_and_b32 s41, s41, 0xffff
	s_mov_b32 s11, 0x20000
	s_mov_b32 s10, 0x9000000
	v_cndmask_b32_e32 v9, 0, v8, vcc
	v_cndmask_b32_e64 v8, 0, v8, s[0:1]
	v_lshlrev_b32_e32 v163, 2, v5
	v_mov_b32_e32 v160, 0
	v_mov_b32_e32 v5, 0xffff
	v_cmp_eq_u32_e64 s[0:1], 0, v4
	s_add_i32 s4, 0, 0x1dc00
	v_cndmask_b32_e64 v3, v3, 1, vcc
	v_lshlrev_b32_e32 v2, 2, v2
	v_cndmask_b32_e64 v183, v9, v5, s[0:1]
	v_or_b32_e32 v185, 64, v184
	s_add_i32 s72, s59, 0x400
	v_or_b32_e32 v186, 64, v182
	s_add_i32 s73, s59, 0x800
	s_add_i32 s74, s59, 0xc00
	v_add3_u32 v187, s59, v6, v7
	v_cndmask_b32_e64 v189, v8, v5, s[2:3]
	v_lshl_add_u32 v190, v1, 2, s4
	v_cndmask_b32_e64 v162, v3, 0, s[0:1]
	v_cmp_gt_u32_e64 s[2:3], 16, v1
	s_bfe_u32 s75, s68, 0x20006
	s_lshl_b32 s76, s57, 4
	s_lshl_b32 s77, s17, 7
	v_lshlrev_b32_e32 v164, 1, v0
	v_mov_b32_e32 v165, v160
	s_mov_b32 s44, s40
	s_mov_b32 s45, s41
	s_mov_b32 s46, s10
	s_mov_b32 s47, s11
	v_lshlrev_b32_e32 v166, 1, v2
	v_mbcnt_hi_u32_b32 v191, -1, v207
	s_branch .LBB0_545

; __device__ __forceinline__ unsigned xb_ld(unsigned* p)              { return __hip_atomic_load(p, __ATOMIC_RELAXED, __HIP_MEMORY_SCOPE_AGENT); }
; __device__ __forceinline__ void xcd_barrier_complete(unsigned* bar, unsigned x, unsigned& nloc, unsigned& nx) {
;     const unsigned G = gridDim.x * gridDim.y * gridDim.z;
;     unsigned sum, cnt, mine, sp = 0u;
;     for (;;) {
;         sum = 0u; cnt = 0u; mine = 0u;
; #pragma unroll
;         for (unsigned j = 0; j < 16; ++j) { const unsigned c = xb_ld(&bar[XB_XCNT(j)]); sum += c; cnt += (c > 0u) ? 1u : 0u; mine = (j == x) ? c : mine; }
; __device__ __forceinline__ void xcd_barrier(const XcdBarrier& b) {
;     asm volatile("s_waitcnt vmcnt(0)" ::: "memory");
;     __syncthreads();
;     if (threadIdx.x == 0) {
;         unsigned* bar = b.bar;
;         __builtin_amdgcn_s_waitcnt(0);
;         unsigned nloc = b.st[0], nx = b.st[1];
;         if (nloc == 0u) { xcd_barrier_complete(bar, b.x, nloc, nx); b.st[0] = nloc; b.st[1] = nx; }
.LBB0_720:
	s_setprio 0
	s_getreg_b32 s2, hwreg(HW_REG_XCC_ID, 0, 4)
	s_waitcnt vmcnt(0)
	s_waitcnt vmcnt(16) lgkmcnt(0)
	s_barrier
	s_and_saveexec_b64 s[0:1], s[92:93]
	s_cbranch_execz .LBB0_772
	s_add_i32 s3, 0, 0x23fc0
	v_mov_b32_e32 v0, s3
	s_waitcnt vmcnt(0) expcnt(0) lgkmcnt(0)
	ds_read_b32 v2, v0
	s_add_i32 s3, 0, 0x23fc4
	v_mov_b32_e32 v0, s3
	ds_read_b32 v0, v0
	s_and_b32 s33, s2, 15
	s_waitcnt lgkmcnt(1)
	v_cmp_ne_u32_e32 vcc, 0, v2
	s_cbranch_vccnz .LBB0_736
	s_add_u32 s2, s18, 0x380200
	s_addc_u32 s3, s19, 0
	s_add_u32 s4, s18, 0x380400
	s_addc_u32 s5, s19, 0
	s_add_u32 s6, s18, 0x380500
	s_addc_u32 s7, s19, 0
	s_add_u32 s8, s18, 0x380600
	s_addc_u32 s9, s19, 0
	s_add_u32 s10, s18, 0x380700
	s_addc_u32 s11, s19, 0
	s_add_u32 s40, s18, 0x380800
	s_addc_u32 s41, s19, 0
	s_add_u32 s42, s18, 0x380900
	s_addc_u32 s43, s19, 0
	s_add_u32 s44, s18, 0x380a00
	s_addc_u32 s45, s19, 0
	s_add_u32 s46, s18, 0x380b00
	s_addc_u32 s47, s19, 0
	s_add_u32 s62, s18, 0x380c00
	s_addc_u32 s63, s19, 0
	s_add_u32 s64, s18, 0x380d00
	s_addc_u32 s65, s19, 0
	s_add_u32 s66, s18, 0x380e00
	s_addc_u32 s67, s19, 0
	s_add_u32 s68, s18, 0x380f00
	s_addc_u32 s69, s19, 0
	s_add_u32 s70, s18, 0x381000
	s_addc_u32 s71, s19, 0
	s_add_u32 s72, s18, 0x381100
	s_addc_u32 s73, s19, 0
	s_add_u32 s74, s18, 0x381200
	s_addc_u32 s75, s19, 0
	s_mul_i32 s48, s95, s17
	s_add_u32 s76, s18, 0x381300
	s_mul_i32 s48, s48, s94
	s_addc_u32 s77, s19, 0
	s_mov_b32 s49, 1
	v_mov_b32_e32 v16, 0
	s_branch .LBB0_724
